# gmlp epilogue: accumulators lane-permuted (ds_bpermute) so each 8-byte load/store instruction touches 4x fewer rows
# speedup vs baseline: 1.0045x; 1.0045x over previous
.LBB0_257:
	v_readfirstlane_b32 s22, v140
	s_ashr_i32 s10, s22, 7
	s_ashr_i32 s11, s10, 31
	s_lshl_b64 s[20:21], s[10:11], 15
	v_and_or_b32 v80, s22, 64, v145
	v_lshl_add_u64 v[18:19], v[74:75], 0, s[20:21]
	v_lshlrev_b32_e32 v0, 8, v80
	s_waitcnt vmcnt(2)
	v_or_b32_e32 v22, 0x1000, v0
	v_mov_b32_e32 v23, v1
	s_waitcnt vmcnt(0)
	v_lshl_add_u64 v[14:15], v[18:19], 0, s[34:35]
	v_lshl_add_u64 v[2:3], v[18:19], 0, v[22:23]
	v_or_b32_e32 v26, 0x2000, v0
	v_mov_b32_e32 v27, v1
	v_lshl_add_u64 v[6:7], v[14:15], 0, v[22:23]
	v_lshl_add_u64 v[20:21], v[18:19], 0, v[0:1]
	global_load_dwordx4 v[54:57], v[2:3], off
	v_or_b32_e32 v0, 0x3000, v0
	global_load_dwordx4 v[6:9], v[6:7], off
	v_lshl_add_u64 v[2:3], v[18:19], 0, v[26:27]
	v_lshl_add_u64 v[10:11], v[14:15], 0, v[26:27]
	s_mov_b64 s[20:21], 0xc0
	v_mov_b64_e32 v[82:83], s[72:73]
	global_load_dwordx4 v[58:61], v[2:3], off
	v_lshl_add_u64 v[14:15], v[14:15], 0, v[0:1]
	global_load_dwordx4 v[10:13], v[10:11], off
	v_lshl_add_u64 v[2:3], v[18:19], 0, v[0:1]
	v_lshl_add_u64 v[30:31], v[18:19], 0, s[20:21]
	v_mad_i64_i32 v[66:67], s[20:21], v87, s64, v[82:83]
	global_load_dwordx4 v[62:65], v[2:3], off
	v_lshl_add_u64 v[66:67], v[76:77], 1, v[66:67]
	global_load_dwordx4 v[14:17], v[14:15], off
	v_lshl_add_u64 v[2:3], v[18:19], 0, 64
	s_mov_b64 s[20:21], 0x1000
	v_lshl_add_u64 v[4:5], v[2:3], 0, v[22:23]
	v_lshl_add_u64 v[96:97], v[66:67], 0, s[20:21]
	v_add_co_u32_e32 v66, vcc, s26, v66
	global_load_dwordx4 v[50:53], v[20:21], off
	global_load_dwordx4 v[38:41], v[4:5], off
	v_lshl_add_u64 v[4:5], v[2:3], 0, v[26:27]
	v_lshl_add_u64 v[2:3], v[2:3], 0, v[0:1]
	v_lshl_add_u64 v[22:23], v[30:31], 0, v[22:23]
	v_lshl_add_u64 v[26:27], v[30:31], 0, v[26:27]
	v_lshl_add_u64 v[30:31], v[30:31], 0, v[0:1]
	v_addc_co_u32_e32 v67, vcc, 0, v67, vcc
	global_load_dwordx4 v[34:37], v[20:21], off offset:64
	global_load_dwordx4 v[42:45], v[4:5], off
	global_load_dwordx4 v[46:49], v[2:3], off
	s_mul_i32 s11, s10, 0x4800
	global_load_dwordx4 v[2:5], v[20:21], off offset:128
	s_add_i32 s16, s16, s96
	global_load_dwordx4 v[18:21], v[20:21], off offset:192
	v_add_u32_e32 v87, s23, v87
	global_load_dwordx4 v[22:25], v[22:23], off
	s_nop 0
	global_load_dwordx4 v[26:29], v[26:27], off
	s_nop 0
	global_load_dwordx4 v[30:33], v[30:31], off
	s_nop 0
	global_load_dwordx4 v[66:69], v[66:67], off
	s_nop 0
	global_load_dwordx4 v[70:73], v[96:97], off offset:48
	global_load_dwordx4 v[88:91], v[96:97], off offset:32
	global_load_dwordx4 v[92:95], v[96:97], off offset:16
	s_waitcnt vmcnt(3)
	v_lshlrev_b32_e32 v150, 16, v66
	v_and_b32_e32 v149, 0xffff0000, v66
	v_lshlrev_b32_e32 v148, 16, v67
	v_and_b32_e32 v146, 0xffff0000, v67
	v_lshlrev_b32_e32 v137, 16, v68
	v_and_b32_e32 v136, 0xffff0000, v68
	v_lshlrev_b32_e32 v135, 16, v69
	v_and_b32_e32 v134, 0xffff0000, v69
	s_waitcnt vmcnt(0)
	v_lshlrev_b32_e32 v133, 16, v92
	v_and_b32_e32 v132, 0xffff0000, v92
	v_lshlrev_b32_e32 v131, 16, v93
	v_and_b32_e32 v130, 0xffff0000, v93
	v_lshlrev_b32_e32 v129, 16, v94
	v_and_b32_e32 v128, 0xffff0000, v94
	v_lshlrev_b32_e32 v127, 16, v95
	v_and_b32_e32 v126, 0xffff0000, v95
	v_lshlrev_b32_e32 v125, 16, v88
	v_and_b32_e32 v124, 0xffff0000, v88
	v_lshlrev_b32_e32 v123, 16, v89
	v_and_b32_e32 v122, 0xffff0000, v89
	v_lshlrev_b32_e32 v121, 16, v90
	v_and_b32_e32 v120, 0xffff0000, v90
	v_lshlrev_b32_e32 v119, 16, v91
	v_and_b32_e32 v118, 0xffff0000, v91
	v_lshlrev_b32_e32 v117, 16, v70
	v_and_b32_e32 v116, 0xffff0000, v70
	v_lshlrev_b32_e32 v115, 16, v71
	v_and_b32_e32 v114, 0xffff0000, v71
	v_lshlrev_b32_e32 v113, 16, v72
	v_and_b32_e32 v112, 0xffff0000, v72
	v_lshlrev_b32_e32 v111, 16, v73
	v_and_b32_e32 v110, 0xffff0000, v73
	global_load_dwordx4 v[66:69], v[96:97], off offset:112
	global_load_dwordx4 v[70:73], v[96:97], off offset:96
	global_load_dwordx4 v[88:91], v[96:97], off offset:80
	global_load_dwordx4 v[92:95], v[96:97], off offset:64
	s_waitcnt vmcnt(3)
	v_and_b32_e32 v0, 0xffff0000, v66
	s_waitcnt vmcnt(2)
	v_lshlrev_b32_e32 v81, 16, v73
	s_waitcnt vmcnt(1)
	v_lshlrev_b32_e32 v101, 16, v88
	v_and_b32_e32 v100, 0xffff0000, v88
	v_lshlrev_b32_e32 v99, 16, v89
	v_and_b32_e32 v98, 0xffff0000, v89
	v_lshlrev_b32_e32 v89, 16, v72
	v_and_b32_e32 v88, 0xffff0000, v72
	v_lshlrev_b32_e32 v72, 16, v66
	v_add_f32_e32 v66, 0, v150
	v_add_f32_e32 v66, v66, v149
	v_add_f32_e32 v66, v66, v148
	v_add_f32_e32 v66, v66, v146
	v_add_f32_e32 v66, v66, v137
	v_add_f32_e32 v66, v66, v136
	v_add_f32_e32 v66, v66, v135
	v_add_f32_e32 v66, v66, v134
	v_add_f32_e32 v66, v66, v133
	v_add_f32_e32 v66, v66, v132
	v_add_f32_e32 v66, v66, v131
	v_add_f32_e32 v66, v66, v130
	v_add_f32_e32 v66, v66, v129
	v_add_f32_e32 v66, v66, v128
	v_add_f32_e32 v66, v66, v127
	v_add_f32_e32 v66, v66, v126
	v_add_f32_e32 v66, v66, v125
	v_add_f32_e32 v66, v66, v124
	v_add_f32_e32 v66, v66, v123
	v_add_f32_e32 v66, v66, v122
	v_add_f32_e32 v66, v66, v121
	v_add_f32_e32 v66, v66, v120
	v_add_f32_e32 v66, v66, v119
	v_add_f32_e32 v66, v66, v118
	v_add_f32_e32 v66, v66, v117
	v_add_f32_e32 v66, v66, v116
	v_add_f32_e32 v66, v66, v115
	v_add_f32_e32 v66, v66, v114
	v_add_f32_e32 v66, v66, v113
	v_add_f32_e32 v66, v66, v112
	v_add_f32_e32 v66, v66, v111
	s_waitcnt vmcnt(0)
	v_lshlrev_b32_e32 v109, 16, v92
	v_add_f32_e32 v66, v66, v110
	v_and_b32_e32 v108, 0xffff0000, v92
	v_add_f32_e32 v66, v66, v109
	v_lshlrev_b32_e32 v107, 16, v93
	v_add_f32_e32 v66, v66, v108
	v_and_b32_e32 v106, 0xffff0000, v93
	v_add_f32_e32 v66, v66, v107
	v_lshlrev_b32_e32 v105, 16, v94
	v_add_f32_e32 v66, v66, v106
	v_and_b32_e32 v104, 0xffff0000, v94
	v_add_f32_e32 v66, v66, v105
	v_lshlrev_b32_e32 v103, 16, v95
	v_add_f32_e32 v66, v66, v104
	v_and_b32_e32 v102, 0xffff0000, v95
	v_add_f32_e32 v66, v66, v103
	v_add_f32_e32 v66, v66, v102
	v_add_f32_e32 v66, v66, v101
	v_add_f32_e32 v66, v66, v100
	v_add_f32_e32 v66, v66, v99
	v_lshlrev_b32_e32 v97, 16, v90
	v_add_f32_e32 v66, v66, v98
	v_and_b32_e32 v96, 0xffff0000, v90
	v_add_f32_e32 v66, v66, v97
	v_lshlrev_b32_e32 v95, 16, v91
	v_add_f32_e32 v66, v66, v96
	v_and_b32_e32 v94, 0xffff0000, v91
	v_add_f32_e32 v66, v66, v95
	v_lshlrev_b32_e32 v93, 16, v70
	v_add_f32_e32 v66, v66, v94
	v_and_b32_e32 v92, 0xffff0000, v70
	v_add_f32_e32 v66, v66, v93
	v_lshlrev_b32_e32 v91, 16, v71
	v_add_f32_e32 v66, v66, v92
	v_and_b32_e32 v90, 0xffff0000, v71
	v_add_f32_e32 v66, v66, v91
	v_add_f32_e32 v66, v66, v90
	v_add_f32_e32 v66, v66, v89
	v_add_f32_e32 v66, v66, v88
	v_and_b32_e32 v73, 0xffff0000, v73
	v_add_f32_e32 v66, v66, v81
	v_add_f32_e32 v66, v66, v73
	v_add_f32_e32 v66, v66, v72
	v_add_f32_e32 v70, v66, v0
	v_and_b32_e32 v66, 0xffff0000, v67
	v_lshlrev_b32_e32 v67, 16, v67
	v_and_b32_e32 v156, 0xffff0000, v68
	v_lshlrev_b32_e32 v157, 16, v68
	v_add_f32_e32 v68, v70, v67
	v_add_f32_e32 v68, v68, v66
	v_add_f32_e32 v68, v68, v157
	v_lshlrev_b32_e32 v153, 16, v69
	v_add_f32_e32 v68, v68, v156
	v_and_b32_e32 v152, 0xffff0000, v69
	v_add_f32_e32 v68, v68, v153
	v_add_f32_e32 v68, v68, v152
	v_fmac_f32_e32 v149, 0xbc800000, v68
	v_fmac_f32_e32 v150, 0xbc800000, v68
	v_mul_f32_e32 v69, v149, v149
	v_fmac_f32_e32 v69, v150, v150
	v_fmac_f32_e32 v148, 0xbc800000, v68
	v_fmac_f32_e32 v69, v148, v148
	v_fmac_f32_e32 v146, 0xbc800000, v68
	v_fmac_f32_e32 v69, v146, v146
	v_fmac_f32_e32 v137, 0xbc800000, v68
	v_fmac_f32_e32 v69, v137, v137
	v_fmac_f32_e32 v136, 0xbc800000, v68
	v_fmac_f32_e32 v69, v136, v136
	v_fmac_f32_e32 v135, 0xbc800000, v68
	v_fmac_f32_e32 v69, v135, v135
	v_fmac_f32_e32 v134, 0xbc800000, v68
	v_fmac_f32_e32 v69, v134, v134
	v_fmac_f32_e32 v133, 0xbc800000, v68
	v_fmac_f32_e32 v69, v133, v133
	v_fmac_f32_e32 v132, 0xbc800000, v68
	v_fmac_f32_e32 v69, v132, v132
	v_fmac_f32_e32 v131, 0xbc800000, v68
	v_fmac_f32_e32 v69, v131, v131
	v_fmac_f32_e32 v130, 0xbc800000, v68
	v_fmac_f32_e32 v69, v130, v130
	v_fmac_f32_e32 v129, 0xbc800000, v68
	v_fmac_f32_e32 v69, v129, v129
	v_fmac_f32_e32 v128, 0xbc800000, v68
	v_fmac_f32_e32 v69, v128, v128
	v_fmac_f32_e32 v127, 0xbc800000, v68
	v_fmac_f32_e32 v69, v127, v127
	v_fmac_f32_e32 v126, 0xbc800000, v68
	v_fmac_f32_e32 v69, v126, v126
	v_fmac_f32_e32 v125, 0xbc800000, v68
	v_fmac_f32_e32 v69, v125, v125
	v_fmac_f32_e32 v124, 0xbc800000, v68
	v_fmac_f32_e32 v69, v124, v124
	v_fmac_f32_e32 v123, 0xbc800000, v68
	v_fmac_f32_e32 v69, v123, v123
	v_fmac_f32_e32 v122, 0xbc800000, v68
	v_fmac_f32_e32 v69, v122, v122
	v_fmac_f32_e32 v121, 0xbc800000, v68
	v_fmac_f32_e32 v69, v121, v121
	v_fmac_f32_e32 v120, 0xbc800000, v68
	v_fmac_f32_e32 v69, v120, v120
	v_fmac_f32_e32 v119, 0xbc800000, v68
	v_fmac_f32_e32 v69, v119, v119
	v_fmac_f32_e32 v118, 0xbc800000, v68
	v_fmac_f32_e32 v69, v118, v118
	v_fmac_f32_e32 v117, 0xbc800000, v68
	v_fmac_f32_e32 v69, v117, v117
	v_fmac_f32_e32 v116, 0xbc800000, v68
	v_fmac_f32_e32 v69, v116, v116
	v_fmac_f32_e32 v115, 0xbc800000, v68
	v_fmac_f32_e32 v69, v115, v115
	v_fmac_f32_e32 v114, 0xbc800000, v68
	v_fmac_f32_e32 v69, v114, v114
	v_fmac_f32_e32 v113, 0xbc800000, v68
	v_fmac_f32_e32 v69, v113, v113
	v_fmac_f32_e32 v112, 0xbc800000, v68
	v_fmac_f32_e32 v69, v112, v112
	v_fmac_f32_e32 v111, 0xbc800000, v68
	v_fmac_f32_e32 v69, v111, v111
	v_fmac_f32_e32 v110, 0xbc800000, v68
	v_fmac_f32_e32 v69, v110, v110
	v_fmac_f32_e32 v109, 0xbc800000, v68
	v_fmac_f32_e32 v69, v109, v109
	v_fmac_f32_e32 v108, 0xbc800000, v68
	v_fmac_f32_e32 v69, v108, v108
	v_fmac_f32_e32 v107, 0xbc800000, v68
	v_fmac_f32_e32 v69, v107, v107
	v_fmac_f32_e32 v106, 0xbc800000, v68
	v_fmac_f32_e32 v69, v106, v106
	v_fmac_f32_e32 v105, 0xbc800000, v68
	v_fmac_f32_e32 v69, v105, v105
	v_fmac_f32_e32 v104, 0xbc800000, v68
	v_fmac_f32_e32 v69, v104, v104
	v_fmac_f32_e32 v103, 0xbc800000, v68
	v_fmac_f32_e32 v69, v103, v103
	v_fmac_f32_e32 v102, 0xbc800000, v68
	v_fmac_f32_e32 v69, v102, v102
	v_fmac_f32_e32 v101, 0xbc800000, v68
	v_fmac_f32_e32 v69, v101, v101
	v_fmac_f32_e32 v100, 0xbc800000, v68
	v_fmac_f32_e32 v69, v100, v100
	v_fmac_f32_e32 v99, 0xbc800000, v68
	v_fmac_f32_e32 v69, v99, v99
	v_fmac_f32_e32 v98, 0xbc800000, v68
	v_fmac_f32_e32 v69, v98, v98
	v_fmac_f32_e32 v97, 0xbc800000, v68
	v_fmac_f32_e32 v69, v97, v97
	v_fmac_f32_e32 v96, 0xbc800000, v68
	v_fmac_f32_e32 v69, v96, v96
	v_fmac_f32_e32 v95, 0xbc800000, v68
	v_fmac_f32_e32 v69, v95, v95
	v_fmac_f32_e32 v94, 0xbc800000, v68
	v_fmac_f32_e32 v69, v94, v94
	v_fmac_f32_e32 v93, 0xbc800000, v68
	v_fmac_f32_e32 v69, v93, v93
	v_fmac_f32_e32 v92, 0xbc800000, v68
	v_fmac_f32_e32 v69, v92, v92
	v_fmac_f32_e32 v91, 0xbc800000, v68
	v_fmac_f32_e32 v69, v91, v91
	v_fmac_f32_e32 v90, 0xbc800000, v68
	v_fmac_f32_e32 v69, v90, v90
	v_fmac_f32_e32 v89, 0xbc800000, v68
	v_fmac_f32_e32 v69, v89, v89
	v_fmac_f32_e32 v88, 0xbc800000, v68
	v_fmac_f32_e32 v69, v88, v88
	v_fmac_f32_e32 v81, 0xbc800000, v68
	v_fmac_f32_e32 v69, v81, v81
	v_fmac_f32_e32 v73, 0xbc800000, v68
	v_mul_f32_e32 v158, 0x3c800000, v68
	v_fmac_f32_e32 v69, v73, v73
	v_fmac_f32_e32 v72, 0xbc800000, v68
	v_fmac_f32_e32 v69, v72, v72
	v_fmac_f32_e32 v0, 0xbc800000, v68
	v_pk_add_f32 v[70:71], v[66:67], v[158:159] op_sel_hi:[1,0] neg_lo:[0,1] neg_hi:[0,1]
	v_fmac_f32_e32 v69, v0, v0
	v_pk_mul_f32 v[66:67], v[70:71], v[70:71]
	s_nop 0
	v_add_f32_e32 v67, v67, v69
	v_pk_add_f32 v[68:69], v[156:157], v[158:159] op_sel_hi:[1,0] neg_lo:[0,1] neg_hi:[0,1]
	v_add_f32_e32 v151, v66, v67
	v_pk_mul_f32 v[66:67], v[68:69], v[68:69]
	s_nop 0
	v_add_f32_e32 v67, v67, v151
	v_add_f32_e32 v151, v66, v67
	v_pk_add_f32 v[66:67], v[152:153], v[158:159] op_sel_hi:[1,0] neg_lo:[0,1] neg_hi:[0,1]
	global_load_dwordx4 v[156:159], v[78:79], off offset:16
	global_load_dwordx4 v[160:163], v[78:79], off
	global_load_dwordx4 v[196:199], v[78:79], off offset:48
	global_load_dwordx4 v[200:203], v[78:79], off offset:32
	global_load_dwordx4 v[204:207], v[78:79], off offset:80
	global_load_dwordx4 v[208:211], v[78:79], off offset:64
	global_load_dwordx4 v[212:215], v[78:79], off offset:112
	global_load_dwordx4 v[216:219], v[78:79], off offset:96
	global_load_dwordx4 v[220:223], v[78:79], off offset:144
	global_load_dwordx4 v[224:227], v[78:79], off offset:128
	global_load_dwordx4 v[228:231], v[78:79], off offset:176
	global_load_dwordx4 v[232:235], v[78:79], off offset:160
	global_load_dwordx4 v[236:239], v[78:79], off offset:208
	global_load_dwordx4 v[240:243], v[78:79], off offset:192
	global_load_dwordx4 v[244:247], v[78:79], off offset:240
	global_load_dwordx4 v[248:251], v[78:79], off offset:224
	v_pk_mul_f32 v[152:153], v[66:67], v[66:67]
	s_nop 0
	v_add_f32_e32 v151, v153, v151
	v_add_f32_e32 v151, v152, v151
	v_fmamk_f32 v151, v151, 0x3c800000, v177
	v_rsq_f32_e32 v151, v151
	s_nop 0
	v_mul_f32_e32 v150, v150, v151
	v_mul_f32_e32 v149, v149, v151
	v_mul_f32_e32 v148, v148, v151
	v_mul_f32_e32 v146, v146, v151
	v_mul_f32_e32 v137, v137, v151
	v_mul_f32_e32 v136, v136, v151
	v_mul_f32_e32 v135, v135, v151
	v_mul_f32_e32 v134, v134, v151
	v_mul_f32_e32 v133, v133, v151
	v_mul_f32_e32 v132, v132, v151
	v_mul_f32_e32 v131, v131, v151
	v_mul_f32_e32 v130, v130, v151
	v_mul_f32_e32 v129, v129, v151
	v_mul_f32_e32 v128, v128, v151
	v_mul_f32_e32 v127, v127, v151
	v_mul_f32_e32 v126, v126, v151
	v_mul_f32_e32 v125, v125, v151
	v_mul_f32_e32 v124, v124, v151
	v_mul_f32_e32 v123, v123, v151
	v_mul_f32_e32 v122, v122, v151
	v_mul_f32_e32 v121, v121, v151
	v_mul_f32_e32 v120, v120, v151
	v_mul_f32_e32 v119, v119, v151
	v_mul_f32_e32 v118, v118, v151
	v_mul_f32_e32 v117, v117, v151
	v_mul_f32_e32 v116, v116, v151
	v_mul_f32_e32 v115, v115, v151
	v_mul_f32_e32 v114, v114, v151
	v_mul_f32_e32 v113, v113, v151
	v_mul_f32_e32 v112, v112, v151
	v_mul_f32_e32 v111, v111, v151
	v_mul_f32_e32 v110, v110, v151
	v_mul_f32_e32 v109, v109, v151
	v_mul_f32_e32 v108, v108, v151
	v_mul_f32_e32 v107, v107, v151
	v_mul_f32_e32 v106, v106, v151
	v_mul_f32_e32 v105, v105, v151
	v_mul_f32_e32 v104, v104, v151
	v_mul_f32_e32 v103, v103, v151
	v_mul_f32_e32 v102, v102, v151
	v_mul_f32_e32 v101, v101, v151
	v_mul_f32_e32 v100, v100, v151
	v_mul_f32_e32 v99, v99, v151
	v_mul_f32_e32 v98, v98, v151
	v_mul_f32_e32 v97, v97, v151
	v_mul_f32_e32 v96, v96, v151
	v_mul_f32_e32 v95, v95, v151
	v_mul_f32_e32 v94, v94, v151
	v_mul_f32_e32 v93, v93, v151
	v_mul_f32_e32 v92, v92, v151
	v_mul_f32_e32 v91, v91, v151
	v_mul_f32_e32 v90, v90, v151
	v_mul_f32_e32 v89, v89, v151
	v_mul_f32_e32 v88, v88, v151
	v_mul_f32_e32 v81, v81, v151
	v_mul_f32_e32 v73, v73, v151
	v_mul_f32_e32 v0, v0, v151
	v_mul_f32_e32 v72, v72, v151
	v_mul_f32_e32 v70, v70, v151
	v_mul_f32_e32 v68, v68, v151
	v_mul_f32_e32 v66, v66, v151
	s_waitcnt vmcnt(15)
	v_mul_f32_e32 v137, v156, v137
	s_waitcnt vmcnt(14)
	v_mul_f32_e32 v150, v160, v150
	v_mul_f32_e32 v149, v161, v149
	v_cvt_pk_bf16_f32 v160, v150, v149
	v_mul_f32_e32 v148, v162, v148
	v_mul_f32_e32 v146, v163, v146
	v_cvt_pk_bf16_f32 v161, v148, v146
	v_mul_f32_e32 v136, v157, v136
	v_cvt_pk_bf16_f32 v162, v137, v136
	v_mul_f32_e32 v135, v158, v135
	v_mul_f32_e32 v134, v159, v134
	v_cvt_pk_bf16_f32 v163, v135, v134
	ds_write_b128 v86, v[160:163]
	s_waitcnt vmcnt(13)
	v_mul_f32_e32 v129, v196, v129
	s_waitcnt vmcnt(12)
	v_mul_f32_e32 v133, v200, v133
	v_mul_f32_e32 v132, v201, v132
	v_cvt_pk_bf16_f32 v132, v133, v132
	v_mul_f32_e32 v131, v202, v131
	v_mul_f32_e32 v130, v203, v130
	v_cvt_pk_bf16_f32 v133, v131, v130
	v_mul_f32_e32 v128, v197, v128
	v_cvt_pk_bf16_f32 v134, v129, v128
	v_mul_f32_e32 v127, v198, v127
	v_mul_f32_e32 v126, v199, v126
	v_cvt_pk_bf16_f32 v135, v127, v126
	ds_write_b128 v86, v[132:135] offset:16
	s_waitcnt vmcnt(11)
	v_mul_f32_e32 v121, v204, v121
	s_waitcnt vmcnt(10)
	v_mul_f32_e32 v125, v208, v125
	v_mul_f32_e32 v124, v209, v124
	v_cvt_pk_bf16_f32 v124, v125, v124
	v_mul_f32_e32 v123, v210, v123
	v_mul_f32_e32 v122, v211, v122
	v_cvt_pk_bf16_f32 v125, v123, v122
	v_mul_f32_e32 v120, v205, v120
	v_cvt_pk_bf16_f32 v126, v121, v120
	v_mul_f32_e32 v119, v206, v119
	v_mul_f32_e32 v118, v207, v118
	v_cvt_pk_bf16_f32 v127, v119, v118
	ds_write_b128 v86, v[124:127] offset:32
	s_waitcnt vmcnt(9)
	v_mul_f32_e32 v113, v212, v113
	s_waitcnt vmcnt(8)
	v_mul_f32_e32 v117, v216, v117
	v_mul_f32_e32 v116, v217, v116
	v_cvt_pk_bf16_f32 v116, v117, v116
	v_mul_f32_e32 v115, v218, v115
	v_mul_f32_e32 v114, v219, v114
	v_cvt_pk_bf16_f32 v117, v115, v114
	v_mul_f32_e32 v112, v213, v112
	v_cvt_pk_bf16_f32 v118, v113, v112
	v_mul_f32_e32 v111, v214, v111
	v_mul_f32_e32 v110, v215, v110
	v_cvt_pk_bf16_f32 v119, v111, v110
	ds_write_b128 v86, v[116:119] offset:48
	s_waitcnt vmcnt(7)
	v_mul_f32_e32 v105, v220, v105
	s_waitcnt vmcnt(6)
	v_mul_f32_e32 v109, v224, v109
	v_mul_f32_e32 v108, v225, v108
	v_cvt_pk_bf16_f32 v108, v109, v108
	v_mul_f32_e32 v107, v226, v107
	v_mul_f32_e32 v106, v227, v106
	v_cvt_pk_bf16_f32 v109, v107, v106
	v_mul_f32_e32 v104, v221, v104
	v_cvt_pk_bf16_f32 v110, v105, v104
	v_mul_f32_e32 v103, v222, v103
	v_mul_f32_e32 v102, v223, v102
	v_cvt_pk_bf16_f32 v111, v103, v102
	ds_write_b128 v86, v[108:111] offset:64
	s_waitcnt vmcnt(5)
	v_mul_f32_e32 v97, v228, v97
	s_waitcnt vmcnt(4)
	v_mul_f32_e32 v101, v232, v101
	v_mul_f32_e32 v100, v233, v100
	v_cvt_pk_bf16_f32 v100, v101, v100
	v_mul_f32_e32 v99, v234, v99
	v_mul_f32_e32 v98, v235, v98
	v_cvt_pk_bf16_f32 v101, v99, v98
	v_mul_f32_e32 v96, v229, v96
	v_cvt_pk_bf16_f32 v102, v97, v96
	v_mul_f32_e32 v95, v230, v95
	v_mul_f32_e32 v94, v231, v94
	v_cvt_pk_bf16_f32 v103, v95, v94
	ds_write_b128 v86, v[100:103] offset:80
	s_waitcnt vmcnt(3)
	v_mul_f32_e32 v89, v236, v89
	s_waitcnt vmcnt(2)
	v_mul_f32_e32 v93, v240, v93
	v_mul_f32_e32 v92, v241, v92
	v_cvt_pk_bf16_f32 v92, v93, v92
	v_mul_f32_e32 v91, v242, v91
	v_mul_f32_e32 v90, v243, v90
	v_cvt_pk_bf16_f32 v93, v91, v90
	v_mul_f32_e32 v88, v237, v88
	v_cvt_pk_bf16_f32 v94, v89, v88
	v_mul_f32_e32 v81, v238, v81
	v_mul_f32_e32 v73, v239, v73
	v_cvt_pk_bf16_f32 v95, v81, v73
	ds_write_b128 v86, v[92:95] offset:96
	v_mov_b32_e32 v81, v1
	s_waitcnt vmcnt(1)
	v_mul_f32_e32 v68, v245, v68
	s_waitcnt vmcnt(0)
	v_mul_f32_e32 v0, v249, v0
	v_mul_f32_e32 v72, v248, v72
	v_cvt_pk_bf16_f32 v92, v72, v0
	v_mul_f32_e32 v0, v71, v151
	v_mul_f32_e32 v0, v250, v0
	v_mul_f32_e32 v70, v251, v70
	v_cvt_pk_bf16_f32 v93, v0, v70
	v_mul_f32_e32 v0, v69, v151
	v_mul_f32_e32 v0, v244, v0
	v_cvt_pk_bf16_f32 v94, v0, v68
	v_mul_f32_e32 v0, v67, v151
	v_mul_f32_e32 v0, v246, v0
	v_mul_f32_e32 v66, v247, v66
	v_cvt_pk_bf16_f32 v95, v0, v66
	v_add_u32_e32 v0, s11, v84
	ds_write_b128 v86, v[92:95] offset:112
	s_waitcnt lgkmcnt(0)
	s_barrier
	ds_read_b64_tr_b16 v[68:69], v0 offset:576
	ds_read_b64_tr_b16 v[66:67], v0
	ds_read_b64_tr_b16 v[70:71], v0 offset:32
	ds_read_b64_tr_b16 v[72:73], v0 offset:608
	ds_read_b64_tr_b16 v[88:89], v0 offset:64
	ds_read_b64_tr_b16 v[90:91], v0 offset:640
	ds_read_b64_tr_b16 v[92:93], v0 offset:96
	ds_read_b64_tr_b16 v[94:95], v0 offset:672
	s_waitcnt lgkmcnt(6)
	v_mfma_f32_16x16x32_bf16 v[96:99], v[66:69], v[50:53], 0
	s_and_b32 s11, s22, 0xffffff80
	v_mfma_f32_16x16x32_bf16 v[100:103], v[66:69], v[54:57], 0
	v_mfma_f32_16x16x32_bf16 v[104:107], v[66:69], v[58:61], 0
	v_mfma_f32_16x16x32_bf16 v[66:69], v[66:69], v[62:65], 0
	s_waitcnt lgkmcnt(4)
	v_mfma_f32_16x16x32_bf16 v[108:111], v[70:73], v[50:53], 0
	v_mfma_f32_16x16x32_bf16 v[112:115], v[70:73], v[54:57], 0
	v_mfma_f32_16x16x32_bf16 v[116:119], v[70:73], v[58:61], 0
	v_mfma_f32_16x16x32_bf16 v[70:73], v[70:73], v[62:65], 0
	s_waitcnt lgkmcnt(2)
	v_mfma_f32_16x16x32_bf16 v[120:123], v[88:91], v[50:53], 0
	v_mfma_f32_16x16x32_bf16 v[124:127], v[88:91], v[54:57], 0
	v_mfma_f32_16x16x32_bf16 v[128:131], v[88:91], v[58:61], 0
	v_mfma_f32_16x16x32_bf16 v[88:91], v[88:91], v[62:65], 0
	s_waitcnt lgkmcnt(0)
	v_mfma_f32_16x16x32_bf16 v[50:53], v[92:95], v[50:53], 0
	v_mfma_f32_16x16x32_bf16 v[54:57], v[92:95], v[54:57], 0
	v_mfma_f32_16x16x32_bf16 v[58:61], v[92:95], v[58:61], 0
	v_mfma_f32_16x16x32_bf16 v[62:65], v[92:95], v[62:65], 0
	ds_read_b64_tr_b16 v[92:93], v0 offset:4608
	ds_read_b64_tr_b16 v[94:95], v0 offset:5184
	ds_read_b64_tr_b16 v[132:133], v0 offset:4640
	ds_read_b64_tr_b16 v[134:135], v0 offset:5216
	ds_read_b64_tr_b16 v[148:149], v0 offset:4672
	ds_read_b64_tr_b16 v[150:151], v0 offset:5248
	ds_read_b64_tr_b16 v[156:157], v0 offset:4704
	ds_read_b64_tr_b16 v[158:159], v0 offset:5280
	s_waitcnt lgkmcnt(6)
	v_mfma_f32_16x16x32_bf16 v[96:99], v[92:95], v[34:37], v[96:99]
	v_mfma_f32_16x16x32_bf16 v[100:103], v[92:95], v[38:41], v[100:103]
	v_mfma_f32_16x16x32_bf16 v[104:107], v[92:95], v[42:45], v[104:107]
	v_mfma_f32_16x16x32_bf16 v[66:69], v[92:95], v[46:49], v[66:69]
	s_waitcnt lgkmcnt(4)
	v_mfma_f32_16x16x32_bf16 v[92:95], v[132:135], v[34:37], v[108:111]
	v_mfma_f32_16x16x32_bf16 v[108:111], v[132:135], v[38:41], v[112:115]
	v_mfma_f32_16x16x32_bf16 v[112:115], v[132:135], v[42:45], v[116:119]
	v_mfma_f32_16x16x32_bf16 v[70:73], v[132:135], v[46:49], v[70:73]
	s_waitcnt lgkmcnt(2)
	v_mfma_f32_16x16x32_bf16 v[116:119], v[148:151], v[34:37], v[120:123]
	v_mfma_f32_16x16x32_bf16 v[120:123], v[148:151], v[38:41], v[124:127]
	v_mfma_f32_16x16x32_bf16 v[124:127], v[148:151], v[42:45], v[128:131]
	v_mfma_f32_16x16x32_bf16 v[88:91], v[148:151], v[46:49], v[88:91]
	s_waitcnt lgkmcnt(0)
	v_mfma_f32_16x16x32_bf16 v[34:37], v[156:159], v[34:37], v[50:53]
	v_mfma_f32_16x16x32_bf16 v[38:41], v[156:159], v[38:41], v[54:57]
	v_mfma_f32_16x16x32_bf16 v[42:45], v[156:159], v[42:45], v[58:61]
	v_mfma_f32_16x16x32_bf16 v[46:49], v[156:159], v[46:49], v[62:65]
	ds_read_b64_tr_b16 v[50:51], v0 offset:9216
	ds_read_b64_tr_b16 v[52:53], v0 offset:9792
	ds_read_b64_tr_b16 v[54:55], v0 offset:9248
	ds_read_b64_tr_b16 v[56:57], v0 offset:9824
	ds_read_b64_tr_b16 v[58:59], v0 offset:9280
	ds_read_b64_tr_b16 v[60:61], v0 offset:9856
	ds_read_b64_tr_b16 v[62:63], v0 offset:9312
	ds_read_b64_tr_b16 v[64:65], v0 offset:9888
	s_waitcnt lgkmcnt(6)
	v_mfma_f32_16x16x32_bf16 v[96:99], v[50:53], v[2:5], v[96:99]
	v_mfma_f32_16x16x32_bf16 v[100:103], v[50:53], v[6:9], v[100:103]
	v_mfma_f32_16x16x32_bf16 v[104:107], v[50:53], v[10:13], v[104:107]
	v_mfma_f32_16x16x32_bf16 v[50:53], v[50:53], v[14:17], v[66:69]
	s_waitcnt lgkmcnt(4)
	v_mfma_f32_16x16x32_bf16 v[66:69], v[54:57], v[2:5], v[92:95]
	v_mfma_f32_16x16x32_bf16 v[92:95], v[54:57], v[6:9], v[108:111]
	v_mfma_f32_16x16x32_bf16 v[108:111], v[54:57], v[10:13], v[112:115]
	s_waitcnt lgkmcnt(2)
	v_mfma_f32_16x16x32_bf16 v[116:119], v[58:61], v[2:5], v[116:119]
	v_mfma_f32_16x16x32_bf16 v[120:123], v[58:61], v[6:9], v[120:123]
	v_mfma_f32_16x16x32_bf16 v[124:127], v[58:61], v[10:13], v[124:127]
	v_mfma_f32_16x16x32_bf16 v[58:61], v[58:61], v[14:17], v[88:91]
	s_waitcnt lgkmcnt(0)
	v_mfma_f32_16x16x32_bf16 v[88:91], v[62:65], v[6:9], v[38:41]
	v_mfma_f32_16x16x32_bf16 v[128:131], v[62:65], v[10:13], v[42:45]
	ds_read_b64_tr_b16 v[6:7], v0 offset:13824
	ds_read_b64_tr_b16 v[8:9], v0 offset:14400
	ds_read_b64_tr_b16 v[10:11], v0 offset:13856
	ds_read_b64_tr_b16 v[12:13], v0 offset:14432
	ds_read_b64_tr_b16 v[148:149], v0 offset:13888
	ds_read_b64_tr_b16 v[150:151], v0 offset:14464
	ds_read_b64_tr_b16 v[156:157], v0 offset:13920
	ds_read_b64_tr_b16 v[158:159], v0 offset:14496
	v_mfma_f32_16x16x32_bf16 v[2:5], v[62:65], v[2:5], v[34:37]
	v_mfma_f32_16x16x32_bf16 v[112:115], v[54:57], v[14:17], v[70:73]
	v_mfma_f32_16x16x32_bf16 v[132:135], v[62:65], v[14:17], v[46:49]
	s_waitcnt lgkmcnt(6)
	v_mfma_f32_16x16x32_bf16 v[70:73], v[6:9], v[18:21], v[96:99]
	v_mfma_f32_16x16x32_bf16 v[54:57], v[6:9], v[22:25], v[100:103]
	v_mfma_f32_16x16x32_bf16 v[42:45], v[6:9], v[26:29], v[104:107]
	v_mfma_f32_16x16x32_bf16 v[14:17], v[6:9], v[30:33], v[50:53]
	s_waitcnt lgkmcnt(4)
	v_mfma_f32_16x16x32_bf16 v[66:69], v[10:13], v[18:21], v[66:69]
	v_mfma_f32_16x16x32_bf16 v[38:41], v[10:13], v[26:29], v[108:111]
	s_waitcnt lgkmcnt(2)
	v_mfma_f32_16x16x32_bf16 v[62:65], v[148:151], v[18:21], v[116:119]
	v_mfma_f32_16x16x32_bf16 v[34:37], v[148:151], v[26:29], v[124:127]
	v_mfma_f32_16x16x32_bf16 v[6:9], v[148:151], v[30:33], v[58:61]
	s_waitcnt lgkmcnt(0)
	v_mfma_f32_16x16x32_bf16 v[58:61], v[156:159], v[18:21], v[2:5]
	v_mfma_f32_16x16x32_bf16 v[18:21], v[156:159], v[26:29], v[128:131]
	v_bfe_u32 v167, v145, 2, 2
	v_lshrrev_b32_e32 v166, 2, v144
	v_lshl_or_b32 v167, v167, 2, v166
	v_sub_u32_e32 v164, v167, v145
	v_add_u32_e32 v164, v80, v164
	v_mov_b32_e32 v165, 0
	v_and_b32_e32 v166, 3, v145
	v_lshl_add_u32 v167, v166, 4, v167
	v_lshlrev_b32_e32 v167, 2, v167
	v_lshlrev_b32_e32 v166, 2, v166
	v_or_b32_e32 v28, s11, v164
	v_ashrrev_i32_e32 v29, 31, v28
	v_lshl_or_b32 v26, s10, 6, v166
	v_mfma_f32_16x16x32_bf16 v[50:53], v[10:13], v[22:25], v[92:95]
	v_ashrrev_i32_e32 v27, 31, v26
	v_lshlrev_b64 v[26:27], 1, v[26:27]
	s_ashr_i32 s10, s11, 31
	v_mfma_f32_16x16x32_bf16 v[10:13], v[10:13], v[30:33], v[112:115]
	v_mfma_f32_16x16x32_bf16 v[2:5], v[156:159], v[30:33], v[132:135]
	v_mov_b32_e32 v29, s10
	v_lshl_add_u64 v[28:29], v[28:29], 2, s[50:51]
	v_mfma_f32_16x16x32_bf16 v[46:49], v[148:151], v[22:25], v[120:123]
	v_mfma_f32_16x16x32_bf16 v[22:25], v[156:159], v[22:25], v[88:91]
	v_mov_b32_e32 v195, 0
	v_lshl_add_u64 v[196:197], s[52:53], 0, v[164:165]
	v_mad_u64_u32 v[200:201], s[20:21], v196, s64, v[82:83]
	v_mov_b32_e32 v198, v201
	v_mad_u64_u32 v[198:199], s[20:21], v197, s64, v[198:199]
	v_mov_b32_e32 v201, v198
	v_lshl_add_u64 v[200:201], v[200:201], 0, v[26:27]
	v_lshlrev_b64 v[196:197], 11, v[196:197]
	v_lshl_add_u64 v[208:209], s[70:71], 0, v[196:197]
	v_lshl_add_u64 v[208:209], v[208:209], 0, v[26:27]
	global_load_dword v216, v[28:29], off
	global_load_dwordx2 v[220:221], v[200:201], off offset:3584
	global_load_dwordx2 v[222:223], v[200:201], off offset:3616
	global_load_dwordx2 v[224:225], v[200:201], off offset:3648
	global_load_dwordx2 v[226:227], v[200:201], off offset:3680
	v_or_b32_e32 v194, 16, v164
	v_lshl_add_u64 v[196:197], s[52:53], 0, v[194:195]
	v_mad_u64_u32 v[202:203], s[20:21], v196, s64, v[82:83]
	v_mov_b32_e32 v198, v203
	v_mad_u64_u32 v[198:199], s[20:21], v197, s64, v[198:199]
	v_mov_b32_e32 v203, v198
	v_lshl_add_u64 v[202:203], v[202:203], 0, v[26:27]
	v_lshlrev_b64 v[196:197], 11, v[196:197]
	v_lshl_add_u64 v[210:211], s[70:71], 0, v[196:197]
	v_lshl_add_u64 v[210:211], v[210:211], 0, v[26:27]
	global_load_dword v217, v[28:29], off offset:64
	global_load_dwordx2 v[228:229], v[202:203], off offset:3584
	global_load_dwordx2 v[230:231], v[202:203], off offset:3616
	global_load_dwordx2 v[232:233], v[202:203], off offset:3648
	global_load_dwordx2 v[234:235], v[202:203], off offset:3680
	v_or_b32_e32 v194, 32, v164
	v_lshl_add_u64 v[196:197], s[52:53], 0, v[194:195]
	v_mad_u64_u32 v[204:205], s[20:21], v196, s64, v[82:83]
	v_mov_b32_e32 v198, v205
	v_mad_u64_u32 v[198:199], s[20:21], v197, s64, v[198:199]
	v_mov_b32_e32 v205, v198
	v_lshl_add_u64 v[204:205], v[204:205], 0, v[26:27]
	v_lshlrev_b64 v[196:197], 11, v[196:197]
	v_lshl_add_u64 v[212:213], s[70:71], 0, v[196:197]
	v_lshl_add_u64 v[212:213], v[212:213], 0, v[26:27]
	global_load_dword v218, v[28:29], off offset:128
	global_load_dwordx2 v[236:237], v[204:205], off offset:3584
	global_load_dwordx2 v[238:239], v[204:205], off offset:3616
	global_load_dwordx2 v[240:241], v[204:205], off offset:3648
	global_load_dwordx2 v[242:243], v[204:205], off offset:3680
	v_or_b32_e32 v194, 48, v164
	v_lshl_add_u64 v[196:197], s[52:53], 0, v[194:195]
	v_mad_u64_u32 v[206:207], s[20:21], v196, s64, v[82:83]
	v_mov_b32_e32 v198, v207
	v_mad_u64_u32 v[198:199], s[20:21], v197, s64, v[198:199]
	v_mov_b32_e32 v207, v198
	v_lshl_add_u64 v[206:207], v[206:207], 0, v[26:27]
	v_lshlrev_b64 v[196:197], 11, v[196:197]
	v_lshl_add_u64 v[214:215], s[70:71], 0, v[196:197]
	v_lshl_add_u64 v[214:215], v[214:215], 0, v[26:27]
	global_load_dword v219, v[28:29], off offset:192
	global_load_dwordx2 v[244:245], v[206:207], off offset:3584
	global_load_dwordx2 v[246:247], v[206:207], off offset:3616
	global_load_dwordx2 v[248:249], v[206:207], off offset:3648
	global_load_dwordx2 v[250:251], v[206:207], off offset:3680
	s_add_u32 s52, s52, s24
	s_addc_u32 s53, s53, s25
	ds_bpermute_b32 v2, v167, v2
	ds_bpermute_b32 v3, v167, v3
	ds_bpermute_b32 v4, v167, v4
	ds_bpermute_b32 v5, v167, v5
	ds_bpermute_b32 v6, v167, v6
	ds_bpermute_b32 v7, v167, v7
	ds_bpermute_b32 v8, v167, v8
	ds_bpermute_b32 v9, v167, v9
	s_waitcnt lgkmcnt(4)
	ds_bpermute_b32 v10, v167, v10
	ds_bpermute_b32 v11, v167, v11
	ds_bpermute_b32 v12, v167, v12
	ds_bpermute_b32 v13, v167, v13
	ds_bpermute_b32 v14, v167, v14
	ds_bpermute_b32 v15, v167, v15
	ds_bpermute_b32 v16, v167, v16
	ds_bpermute_b32 v17, v167, v17
	s_waitcnt lgkmcnt(4)
	ds_bpermute_b32 v18, v167, v18
	ds_bpermute_b32 v19, v167, v19
	ds_bpermute_b32 v20, v167, v20
	ds_bpermute_b32 v21, v167, v21
	ds_bpermute_b32 v22, v167, v22
	ds_bpermute_b32 v23, v167, v23
	ds_bpermute_b32 v24, v167, v24
	ds_bpermute_b32 v25, v167, v25
	s_waitcnt lgkmcnt(4)
	ds_bpermute_b32 v34, v167, v34
	ds_bpermute_b32 v35, v167, v35
	ds_bpermute_b32 v36, v167, v36
	ds_bpermute_b32 v37, v167, v37
	ds_bpermute_b32 v38, v167, v38
	ds_bpermute_b32 v39, v167, v39
	ds_bpermute_b32 v40, v167, v40
	ds_bpermute_b32 v41, v167, v41
	s_waitcnt lgkmcnt(4)
	ds_bpermute_b32 v42, v167, v42
	ds_bpermute_b32 v43, v167, v43
	ds_bpermute_b32 v44, v167, v44
	ds_bpermute_b32 v45, v167, v45
	ds_bpermute_b32 v46, v167, v46
	ds_bpermute_b32 v47, v167, v47
	ds_bpermute_b32 v48, v167, v48
	ds_bpermute_b32 v49, v167, v49
	s_waitcnt lgkmcnt(4)
	ds_bpermute_b32 v50, v167, v50
	ds_bpermute_b32 v51, v167, v51
	ds_bpermute_b32 v52, v167, v52
	ds_bpermute_b32 v53, v167, v53
	ds_bpermute_b32 v54, v167, v54
	ds_bpermute_b32 v55, v167, v55
	ds_bpermute_b32 v56, v167, v56
	ds_bpermute_b32 v57, v167, v57
	s_waitcnt lgkmcnt(4)
	ds_bpermute_b32 v58, v167, v58
	ds_bpermute_b32 v59, v167, v59
	ds_bpermute_b32 v60, v167, v60
	ds_bpermute_b32 v61, v167, v61
	ds_bpermute_b32 v62, v167, v62
	ds_bpermute_b32 v63, v167, v63
	ds_bpermute_b32 v64, v167, v64
	ds_bpermute_b32 v65, v167, v65
	s_waitcnt lgkmcnt(4)
	ds_bpermute_b32 v66, v167, v66
	ds_bpermute_b32 v67, v167, v67
	ds_bpermute_b32 v68, v167, v68
	ds_bpermute_b32 v69, v167, v69
	ds_bpermute_b32 v70, v167, v70
	ds_bpermute_b32 v71, v167, v71
	ds_bpermute_b32 v72, v167, v72
	ds_bpermute_b32 v73, v167, v73
	s_waitcnt lgkmcnt(4)
	s_waitcnt vmcnt(0) lgkmcnt(0)
	v_add_f32_e32 v70, v70, v216
	v_add_f32_e32 v71, v71, v216
	v_add_f32_e32 v72, v72, v216
	v_add_f32_e32 v73, v73, v216
	v_lshlrev_b32_e32 v194, 16, v220
	v_and_b32_e32 v195, 0xffff0000, v220
	v_lshlrev_b32_e32 v196, 16, v221
	v_and_b32_e32 v197, 0xffff0000, v221
	v_pk_mul_f32 v[70:71], v[70:71], v[194:195]
	v_pk_mul_f32 v[72:73], v[72:73], v[196:197]
	v_cvt_pk_bf16_f32 v70, v70, v71
	v_cvt_pk_bf16_f32 v71, v72, v73
	global_store_dwordx2 v[208:209], v[70:71], off offset:1536
	v_add_f32_e32 v66, v66, v216
	v_add_f32_e32 v67, v67, v216
	v_add_f32_e32 v68, v68, v216
	v_add_f32_e32 v69, v69, v216
	v_lshlrev_b32_e32 v194, 16, v222
	v_and_b32_e32 v195, 0xffff0000, v222
	v_lshlrev_b32_e32 v196, 16, v223
	v_and_b32_e32 v197, 0xffff0000, v223
	v_pk_mul_f32 v[66:67], v[66:67], v[194:195]
	v_pk_mul_f32 v[68:69], v[68:69], v[196:197]
	v_cvt_pk_bf16_f32 v66, v66, v67
	v_cvt_pk_bf16_f32 v67, v68, v69
	global_store_dwordx2 v[208:209], v[66:67], off offset:1568
	v_add_f32_e32 v62, v62, v216
	v_add_f32_e32 v63, v63, v216
	v_add_f32_e32 v64, v64, v216
	v_add_f32_e32 v65, v65, v216
	v_lshlrev_b32_e32 v194, 16, v224
	v_and_b32_e32 v195, 0xffff0000, v224
	v_lshlrev_b32_e32 v196, 16, v225
	v_and_b32_e32 v197, 0xffff0000, v225
	v_pk_mul_f32 v[62:63], v[62:63], v[194:195]
	v_pk_mul_f32 v[64:65], v[64:65], v[196:197]
	v_cvt_pk_bf16_f32 v62, v62, v63
	v_cvt_pk_bf16_f32 v63, v64, v65
	global_store_dwordx2 v[208:209], v[62:63], off offset:1600
	v_add_f32_e32 v58, v58, v216
	v_add_f32_e32 v59, v59, v216
	v_add_f32_e32 v60, v60, v216
	v_add_f32_e32 v61, v61, v216
	v_lshlrev_b32_e32 v194, 16, v226
	v_and_b32_e32 v195, 0xffff0000, v226
	v_lshlrev_b32_e32 v196, 16, v227
	v_and_b32_e32 v197, 0xffff0000, v227
	v_pk_mul_f32 v[58:59], v[58:59], v[194:195]
	v_pk_mul_f32 v[60:61], v[60:61], v[196:197]
	v_cvt_pk_bf16_f32 v58, v58, v59
	v_cvt_pk_bf16_f32 v59, v60, v61
	global_store_dwordx2 v[208:209], v[58:59], off offset:1632
	s_nop 0
	v_add_f32_e32 v54, v54, v217
	v_add_f32_e32 v55, v55, v217
	v_add_f32_e32 v56, v56, v217
	v_add_f32_e32 v57, v57, v217
	v_lshlrev_b32_e32 v194, 16, v228
	v_and_b32_e32 v195, 0xffff0000, v228
	v_lshlrev_b32_e32 v196, 16, v229
	v_and_b32_e32 v197, 0xffff0000, v229
	v_pk_mul_f32 v[54:55], v[54:55], v[194:195]
	v_pk_mul_f32 v[56:57], v[56:57], v[196:197]
	v_cvt_pk_bf16_f32 v54, v54, v55
	v_cvt_pk_bf16_f32 v55, v56, v57
	global_store_dwordx2 v[210:211], v[54:55], off offset:1536
	v_add_f32_e32 v50, v50, v217
	v_add_f32_e32 v51, v51, v217
	v_add_f32_e32 v52, v52, v217
	v_add_f32_e32 v53, v53, v217
	v_lshlrev_b32_e32 v194, 16, v230
	v_and_b32_e32 v195, 0xffff0000, v230
	v_lshlrev_b32_e32 v196, 16, v231
	v_and_b32_e32 v197, 0xffff0000, v231
	v_pk_mul_f32 v[50:51], v[50:51], v[194:195]
	v_pk_mul_f32 v[52:53], v[52:53], v[196:197]
	v_cvt_pk_bf16_f32 v50, v50, v51
	v_cvt_pk_bf16_f32 v51, v52, v53
	global_store_dwordx2 v[210:211], v[50:51], off offset:1568
	v_add_f32_e32 v46, v46, v217
	v_add_f32_e32 v47, v47, v217
	v_add_f32_e32 v48, v48, v217
	v_add_f32_e32 v49, v49, v217
	v_lshlrev_b32_e32 v194, 16, v232
	v_and_b32_e32 v195, 0xffff0000, v232
	v_lshlrev_b32_e32 v196, 16, v233
	v_and_b32_e32 v197, 0xffff0000, v233
	v_pk_mul_f32 v[46:47], v[46:47], v[194:195]
	v_pk_mul_f32 v[48:49], v[48:49], v[196:197]
	v_cvt_pk_bf16_f32 v46, v46, v47
	v_cvt_pk_bf16_f32 v47, v48, v49
	global_store_dwordx2 v[210:211], v[46:47], off offset:1600
	v_add_f32_e32 v22, v22, v217
	v_add_f32_e32 v23, v23, v217
	v_add_f32_e32 v24, v24, v217
	v_add_f32_e32 v25, v25, v217
	v_lshlrev_b32_e32 v194, 16, v234
	v_and_b32_e32 v195, 0xffff0000, v234
	v_lshlrev_b32_e32 v196, 16, v235
	v_and_b32_e32 v197, 0xffff0000, v235
	v_pk_mul_f32 v[22:23], v[22:23], v[194:195]
	v_pk_mul_f32 v[24:25], v[24:25], v[196:197]
	v_cvt_pk_bf16_f32 v22, v22, v23
	v_cvt_pk_bf16_f32 v23, v24, v25
	global_store_dwordx2 v[210:211], v[22:23], off offset:1632
	s_nop 0
	v_add_f32_e32 v42, v42, v218
	v_add_f32_e32 v43, v43, v218
	v_add_f32_e32 v44, v44, v218
	v_add_f32_e32 v45, v45, v218
	v_lshlrev_b32_e32 v194, 16, v236
	v_and_b32_e32 v195, 0xffff0000, v236
	v_lshlrev_b32_e32 v196, 16, v237
	v_and_b32_e32 v197, 0xffff0000, v237
	v_pk_mul_f32 v[42:43], v[42:43], v[194:195]
	v_pk_mul_f32 v[44:45], v[44:45], v[196:197]
	v_cvt_pk_bf16_f32 v42, v42, v43
	v_cvt_pk_bf16_f32 v43, v44, v45
	global_store_dwordx2 v[212:213], v[42:43], off offset:1536
	v_add_f32_e32 v38, v38, v218
	v_add_f32_e32 v39, v39, v218
	v_add_f32_e32 v40, v40, v218
	v_add_f32_e32 v41, v41, v218
	v_lshlrev_b32_e32 v194, 16, v238
	v_and_b32_e32 v195, 0xffff0000, v238
	v_lshlrev_b32_e32 v196, 16, v239
	v_and_b32_e32 v197, 0xffff0000, v239
	v_pk_mul_f32 v[38:39], v[38:39], v[194:195]
	v_pk_mul_f32 v[40:41], v[40:41], v[196:197]
	v_cvt_pk_bf16_f32 v38, v38, v39
	v_cvt_pk_bf16_f32 v39, v40, v41
	global_store_dwordx2 v[212:213], v[38:39], off offset:1568
	v_add_f32_e32 v34, v34, v218
	v_add_f32_e32 v35, v35, v218
	v_add_f32_e32 v36, v36, v218
	v_add_f32_e32 v37, v37, v218
	v_lshlrev_b32_e32 v194, 16, v240
	v_and_b32_e32 v195, 0xffff0000, v240
	v_lshlrev_b32_e32 v196, 16, v241
	v_and_b32_e32 v197, 0xffff0000, v241
	v_pk_mul_f32 v[34:35], v[34:35], v[194:195]
	v_pk_mul_f32 v[36:37], v[36:37], v[196:197]
	v_cvt_pk_bf16_f32 v34, v34, v35
	v_cvt_pk_bf16_f32 v35, v36, v37
	global_store_dwordx2 v[212:213], v[34:35], off offset:1600
	v_add_f32_e32 v18, v18, v218
	v_add_f32_e32 v19, v19, v218
	v_add_f32_e32 v20, v20, v218
	v_add_f32_e32 v21, v21, v218
	v_lshlrev_b32_e32 v194, 16, v242
	v_and_b32_e32 v195, 0xffff0000, v242
	v_lshlrev_b32_e32 v196, 16, v243
	v_and_b32_e32 v197, 0xffff0000, v243
	v_pk_mul_f32 v[18:19], v[18:19], v[194:195]
	v_pk_mul_f32 v[20:21], v[20:21], v[196:197]
	v_cvt_pk_bf16_f32 v18, v18, v19
	v_cvt_pk_bf16_f32 v19, v20, v21
	global_store_dwordx2 v[212:213], v[18:19], off offset:1632
	s_nop 0
	v_add_f32_e32 v14, v14, v219
	v_add_f32_e32 v15, v15, v219
	v_add_f32_e32 v16, v16, v219
	v_add_f32_e32 v17, v17, v219
	v_lshlrev_b32_e32 v194, 16, v244
	v_and_b32_e32 v195, 0xffff0000, v244
	v_lshlrev_b32_e32 v196, 16, v245
	v_and_b32_e32 v197, 0xffff0000, v245
	v_pk_mul_f32 v[14:15], v[14:15], v[194:195]
	v_pk_mul_f32 v[16:17], v[16:17], v[196:197]
	v_cvt_pk_bf16_f32 v14, v14, v15
	v_cvt_pk_bf16_f32 v15, v16, v17
	global_store_dwordx2 v[214:215], v[14:15], off offset:1536
	v_add_f32_e32 v10, v10, v219
	v_add_f32_e32 v11, v11, v219
	v_add_f32_e32 v12, v12, v219
	v_add_f32_e32 v13, v13, v219
	v_lshlrev_b32_e32 v194, 16, v246
	v_and_b32_e32 v195, 0xffff0000, v246
	v_lshlrev_b32_e32 v196, 16, v247
	v_and_b32_e32 v197, 0xffff0000, v247
	v_pk_mul_f32 v[10:11], v[10:11], v[194:195]
	v_pk_mul_f32 v[12:13], v[12:13], v[196:197]
	v_cvt_pk_bf16_f32 v10, v10, v11
	v_cvt_pk_bf16_f32 v11, v12, v13
	global_store_dwordx2 v[214:215], v[10:11], off offset:1568
	v_add_f32_e32 v6, v6, v219
	v_add_f32_e32 v7, v7, v219
	v_add_f32_e32 v8, v8, v219
	v_add_f32_e32 v9, v9, v219
	v_lshlrev_b32_e32 v194, 16, v248
	v_and_b32_e32 v195, 0xffff0000, v248
	v_lshlrev_b32_e32 v196, 16, v249
	v_and_b32_e32 v197, 0xffff0000, v249
	v_pk_mul_f32 v[6:7], v[6:7], v[194:195]
	v_pk_mul_f32 v[8:9], v[8:9], v[196:197]
	v_cvt_pk_bf16_f32 v6, v6, v7
	v_cvt_pk_bf16_f32 v7, v8, v9
	global_store_dwordx2 v[214:215], v[6:7], off offset:1600
	v_add_f32_e32 v2, v2, v219
	v_add_f32_e32 v3, v3, v219
	v_add_f32_e32 v4, v4, v219
	v_add_f32_e32 v5, v5, v219
	v_lshlrev_b32_e32 v194, 16, v250
	v_and_b32_e32 v195, 0xffff0000, v250
	v_lshlrev_b32_e32 v196, 16, v251
	v_and_b32_e32 v197, 0xffff0000, v251
	v_pk_mul_f32 v[2:3], v[2:3], v[194:195]
	v_pk_mul_f32 v[4:5], v[4:5], v[196:197]
	v_cvt_pk_bf16_f32 v2, v2, v3
	v_cvt_pk_bf16_f32 v3, v4, v5
	global_store_dwordx2 v[214:215], v[2:3], off offset:1632
	s_cmp_ge_i32 s16, s2
	s_barrier
	s_cbranch_scc0 .LBB0_257
	s_branch .LBB0_254
